# v54 stack + SSD loop: redundant s[60:67] readlane reloads dropped, sum-of-squares xor-butterfly via DPP adds instead of ds_bpermute
# baseline (speedup 1.0000x reference)
; __device__ __forceinline__ void phase_ssd(const Params& p, uchar* sm, int j, bf16_t* zx, const float* dtraw, float* ssqb) {
;     ...
;             if (tabw) {
;                 const float v = dtr + dtb;
;                 const float dt = v > 20.f ? v : log1pf(__expf(v));
;                 const float cs = wave_incl_scan(dt * a_coef);
;                 const float c63 = __int_as_float(__builtin_amdgcn_readlane(__float_as_int(cs), 63));
;                 dtL[th * 64 + lane] = dt; csL[th * 64 + lane] = cs; e1L[th * 64 + lane] = __expf(cs); e2L[th * 64 + lane] = dt * __expf(c63 - cs);
;                 if (c + 1 < 32) dtr = dtraw[(zrow0 + 64 + lane) * 32 + headA + th];
.LBB0_473:
	s_or_b64 exec, exec, s[68:69]
	v_mul_f32_e32 v107, v228, v106
	v_mov_b32_e32 v108, 0
	s_andn2_b64 vcc, exec, s[0:1]
	s_nop 0
	v_mov_b32_dpp v108, v107 row_shr:1 row_mask:0xf bank_mask:0xf
	v_fmac_f32_e32 v108, v228, v106
	s_nop 1
	v_add_f32_dpp v107, v108, v108 row_shr:2 row_mask:0xf bank_mask:0xf bound_ctrl:1
	v_mov_b32_e32 v108, 0
	s_nop 0
	v_add_f32_dpp v107, v107, v107 row_shr:4 row_mask:0xf bank_mask:0xf bound_ctrl:1
	s_nop 1
	v_add_f32_dpp v107, v107, v107 row_shr:8 row_mask:0xf bank_mask:0xf bound_ctrl:1
	s_nop 1
	v_mov_b32_dpp v108, v107 row_bcast:15 row_mask:0xa bank_mask:0xf
	v_add_f32_e32 v107, v107, v108
	v_mov_b32_e32 v108, 0
	s_nop 1
	v_mov_b32_dpp v108, v107 row_bcast:31 row_mask:0xc bank_mask:0xf
	v_add_f32_e32 v107, v107, v108
	ds_write_b32 v189, v106
	ds_write_b32 v190, v107
	v_readlane_b32 s68, v107, 63
	v_mul_f32_e32 v108, 0x3fb8aa3b, v107
	v_exp_f32_e32 v108, v108
	v_sub_f32_e32 v107, s68, v107
	v_mul_f32_e32 v107, 0x3fb8aa3b, v107
	v_exp_f32_e32 v107, v107
	ds_write_b32 v191, v108
	v_mul_f32_e32 v106, v106, v107
	ds_write_b32 v192, v106
	s_cbranch_vccnz .LBB0_475
	v_lshl_add_u64 v[106:107], s[66:67], 0, v[2:3]
	global_load_dword v1, v[106:107], off

; __device__ __forceinline__ void phase_ssd(const Params& p, uchar* sm, int j, bf16_t* zx, const float* dtraw, float* ssqb) {
;     ...
;                 uchar* stw = sm + L_ST + w * (16 * RS_CB);
; #pragma unroll
;                 for (int n = 0; n < 8; ++n) { u32x2 o; o.x = pk2(st[n][0], st[n][1]); o.y = pk2(st[n][2], st[n][3]);
;                     *(u32x2*)(stw + l15 * RS_CB + (n * 16 + quad * 4) * 2) = o; }
; #pragma unroll
;                 for (int m = 0; m < 4; ++m) yacc[m] = (f32x4){0.f, 0.f, 0.f, 0.f};
; #pragma unroll
;                 for (int ks = 0; ks < 4; ++ks) {
;                     const bf16x8 bfr = *(const bf16x8*)(stw + l15 * RS_CB + (ks * 32 + quad * 8) * 2);
; #pragma unroll
;                     for (int m = 0; m < 4; ++m) { const bf16x8 afr = *(const bf16x8*)(sm + L_C + (m * 16 + l15) * RS_CB + (ks * 32 + quad * 8) * 2);
;                         yacc[m] = __builtin_amdgcn_mfma_f32_16x16x32_bf16(afr, bfr, yacc[m], 0, 0, 0); }
;                 }
; #pragma unroll
;                 for (int m = 0; m < 4; ++m) { const f32x4 ev = *(const f32x4*)(e1L + rl * 64 + m * 16 + quad * 4);
; #pragma unroll
;                     for (int r = 0; r < 4; ++r) yacc[m][r] *= ev[r]; }
;                 const float cs63 = csL[rl * 64 + 63];
;                 bf16x8 xdt[2], xdd[2];
; #pragma unroll
;                 for (int ks = 0; ks < 2; ++ks) {
;                     float xr[8]; unpack8(*(const u32x4*)(sm + L_XT + (chl + l15) * RS_T + (((ks * 16 + quad * 4) ^ (4 * w)) * 4)), xr);
;                     const f32x4 d0 = *(const f32x4*)(dtL + rl * 64 + ks * 32 + quad * 8), d1 = *(const f32x4*)(dtL + rl * 64 + ks * 32 + quad * 8 + 4);
;                     const f32x4 g0 = *(const f32x4*)(e2L + rl * 64 + ks * 32 + quad * 8), g1 = *(const f32x4*)(e2L + rl * 64 + ks * 32 + quad * 8 + 4);
;                     float a[8], b[8];
; #pragma unroll
;                     for (int i = 0; i < 4; ++i) { a[i] = xr[i] * d0[i]; a[4 + i] = xr[4 + i] * d1[i]; b[i] = xr[i] * g0[i]; b[4 + i] = xr[4 + i] * g1[i]; }
;                     const u32x4 pa = pack8(a), pb = pack8(b);
;                     xdt[ks] = __builtin_bit_cast(bf16x8, pa); xdd[ks] = __builtin_bit_cast(bf16x8, pb);
;                 }
;                 __syncthreads();
.LBB0_477:
	s_or_b64 exec, exec, s[4:5]
	v_cvt_pk_bf16_f32 v104, v72, v73
	v_cvt_pk_bf16_f32 v105, v74, v75
	v_add_u32_e32 v108, v200, v194
	v_cvt_pk_bf16_f32 v106, v76, v77
	v_cvt_pk_bf16_f32 v107, v78, v79
	ds_write2_b64 v108, v[104:105], v[106:107] offset1:4
	v_cvt_pk_bf16_f32 v104, v64, v65
	v_cvt_pk_bf16_f32 v105, v66, v67
	v_cvt_pk_bf16_f32 v106, v68, v69
	v_cvt_pk_bf16_f32 v107, v70, v71
	ds_write2_b64 v108, v[104:105], v[106:107] offset0:8 offset1:12
	v_cvt_pk_bf16_f32 v104, v92, v93
	v_cvt_pk_bf16_f32 v105, v94, v95
	v_cvt_pk_bf16_f32 v106, v80, v81
	v_cvt_pk_bf16_f32 v107, v82, v83
	ds_write2_b64 v108, v[104:105], v[106:107] offset0:16 offset1:20
	v_cvt_pk_bf16_f32 v104, v84, v85
	v_cvt_pk_bf16_f32 v105, v86, v87
	v_cvt_pk_bf16_f32 v106, v88, v89
	v_cvt_pk_bf16_f32 v107, v90, v91
	ds_write2_b64 v108, v[104:105], v[106:107] offset0:24 offset1:28
	v_add_u32_e32 v128, v200, v188
	ds_read_b128 v[104:107], v128
	v_add_u32_e32 v129, v204, v199
	ds_read_b128 v[108:111], v129
	ds_read_b128 v[112:115], v216
	ds_read_b128 v[116:119], v216 offset:4352
	ds_read_b128 v[120:123], v216 offset:8704
	ds_read_b128 v[132:135], v128 offset:64
	ds_read_b128 v[124:127], v129 offset:64
	ds_read_b128 v[240:243], v216 offset:64
	ds_read_b128 v[244:247], v216 offset:4416
	ds_read_b128 v[248:251], v216 offset:8768
	s_waitcnt lgkmcnt(7)
	v_mfma_f32_16x16x32_bf16 v[108:111], v[108:111], v[104:107], 0
	s_andn2_b64 vcc, exec, s[0:1]
	v_mfma_f32_16x16x32_bf16 v[112:115], v[112:115], v[104:107], 0
	s_waitcnt lgkmcnt(5)
	v_mfma_f32_16x16x32_bf16 v[116:119], v[116:119], v[104:107], 0
	v_mfma_f32_16x16x32_bf16 v[104:107], v[120:123], v[104:107], 0
	ds_read_b128 v[120:123], v128 offset:128
	s_waitcnt lgkmcnt(4)
	v_mfma_f32_16x16x32_bf16 v[108:111], v[124:127], v[132:135], v[108:111]
	ds_read_b128 v[124:127], v129 offset:128
	s_waitcnt lgkmcnt(4)
	v_mfma_f32_16x16x32_bf16 v[112:115], v[240:243], v[132:135], v[112:115]
	ds_read_b128 v[240:243], v216 offset:128
	s_waitcnt lgkmcnt(4)
	v_mfma_f32_16x16x32_bf16 v[116:119], v[244:247], v[132:135], v[116:119]
	ds_read_b128 v[244:247], v216 offset:4480
	s_waitcnt lgkmcnt(4)
	v_mfma_f32_16x16x32_bf16 v[104:107], v[248:251], v[132:135], v[104:107]
	ds_read_b128 v[132:135], v216 offset:8832
	ds_read_b128 v[248:251], v128 offset:192
	s_waitcnt lgkmcnt(4)
	v_mfma_f32_16x16x32_bf16 v[108:111], v[124:127], v[120:123], v[108:111]
	ds_read_b128 v[124:127], v129 offset:192
	s_waitcnt lgkmcnt(4)
	v_mfma_f32_16x16x32_bf16 v[112:115], v[240:243], v[120:123], v[112:115]
	ds_read_b128 v[240:243], v216 offset:192
	s_waitcnt lgkmcnt(4)
	v_mfma_f32_16x16x32_bf16 v[116:119], v[244:247], v[120:123], v[116:119]
	ds_read_b128 v[244:247], v216 offset:4544
	s_waitcnt lgkmcnt(4)
	v_mfma_f32_16x16x32_bf16 v[104:107], v[132:135], v[120:123], v[104:107]
	ds_read_b128 v[128:131], v216 offset:8896
	ds_read_b128 v[120:123], v217
	ds_read_b128 v[132:135], v217 offset:64
	s_waitcnt lgkmcnt(5)
	v_mfma_f32_16x16x32_bf16 v[108:111], v[124:127], v[248:251], v[108:111]
	ds_read_b128 v[124:127], v217 offset:128
	s_waitcnt lgkmcnt(5)
	v_mfma_f32_16x16x32_bf16 v[112:115], v[240:243], v[248:251], v[112:115]
	ds_read_b128 v[240:243], v217 offset:192
	s_waitcnt lgkmcnt(4)
	v_mfma_f32_16x16x32_bf16 v[116:119], v[244:247], v[248:251], v[116:119]
	v_mfma_f32_16x16x32_bf16 v[104:107], v[128:131], v[248:251], v[104:107]
	ds_read_b128 v[248:251], v218 offset:53248
	s_waitcnt lgkmcnt(3)
	v_pk_mul_f32 v[110:111], v[110:111], v[122:123]
	s_nop 0
	v_pk_mul_f32 v[114:115], v[114:115], v[134:135]
	v_pk_mul_f32 v[112:113], v[112:113], v[132:133]
	v_pk_mul_f32 v[108:109], v[108:109], v[120:121]
	ds_read_b128 v[120:123], v201
	s_waitcnt lgkmcnt(3)
	v_pk_mul_f32 v[118:119], v[118:119], v[126:127]
	v_pk_mul_f32 v[116:117], v[116:117], v[124:125]
	ds_read_b128 v[124:127], v201 offset:16
	ds_read_b128 v[132:135], v202
	s_waitcnt lgkmcnt(4)
	v_pk_mul_f32 v[130:131], v[106:107], v[242:243]
	v_pk_mul_f32 v[128:129], v[104:105], v[240:241]
	ds_read_b128 v[238:241], v202 offset:16
	s_waitcnt lgkmcnt(4)
	v_lshlrev_b32_e32 v139, 16, v248
	v_and_b32_e32 v170, 0xffff0000, v248
	v_lshlrev_b32_e32 v237, 16, v249
	v_and_b32_e32 v242, 0xffff0000, v249
	v_lshlrev_b32_e32 v243, 16, v250
	v_and_b32_e32 v244, 0xffff0000, v250
	v_lshlrev_b32_e32 v245, 16, v251
	v_and_b32_e32 v246, 0xffff0000, v251
	s_waitcnt lgkmcnt(2)
	v_mul_f32_e32 v122, v122, v237
	v_mul_f32_e32 v124, v124, v243
	v_mul_f32_e32 v125, v125, v244
	v_mul_f32_e32 v126, v126, v245
	v_mul_f32_e32 v127, v127, v246
	s_waitcnt lgkmcnt(1)
	v_mul_f32_e32 v237, v134, v237
	v_mul_f32_e32 v123, v123, v242
	v_mul_f32_e32 v242, v135, v242
	v_cvt_pk_bf16_f32 v134, v124, v125
	v_cvt_pk_bf16_f32 v135, v126, v127
	ds_read_b128 v[124:127], v219 offset:53248
	v_mul_f32_e32 v120, v120, v139
	v_mul_f32_e32 v139, v132, v139
	s_waitcnt lgkmcnt(1)
	v_mul_f32_e32 v238, v238, v243
	v_mul_f32_e32 v121, v121, v170
	v_mul_f32_e32 v170, v133, v170
	v_mul_f32_e32 v239, v239, v244
	v_mul_f32_e32 v240, v240, v245
	v_mul_f32_e32 v241, v241, v246
	v_cvt_pk_bf16_f32 v132, v120, v121
	v_cvt_pk_bf16_f32 v133, v122, v123
	v_cvt_pk_bf16_f32 v104, v139, v170
	v_cvt_pk_bf16_f32 v105, v237, v242
	v_cvt_pk_bf16_f32 v106, v238, v239
	v_cvt_pk_bf16_f32 v107, v240, v241
	s_waitcnt lgkmcnt(0)
	v_lshlrev_b32_e32 v139, 16, v124
	v_and_b32_e32 v170, 0xffff0000, v124
	v_lshlrev_b32_e32 v237, 16, v125
	v_and_b32_e32 v250, 0xffff0000, v125
	v_lshlrev_b32_e32 v251, 16, v126
	v_and_b32_e32 v252, 0xffff0000, v126
	v_lshlrev_b32_e32 v253, 16, v127
	v_and_b32_e32 v182, 0xffff0000, v127
	ds_read_b128 v[124:127], v201 offset:128
	ds_read_b128 v[238:241], v201 offset:144
	ds_read_b128 v[242:245], v202 offset:128
	ds_read_b128 v[246:249], v202 offset:144
	s_waitcnt lgkmcnt(0)
	s_barrier
; __device__ __forceinline__ void phase_ssd(const Params& p, uchar* sm, int j, bf16_t* zx, const float* dtraw, float* ssqb) {
;     ...
;                 for (int ks = 0; ks < 2; ++ks)
; #pragma unroll
;                     for (int m = 0; m < 4; ++m) {
;                         if (ks == 1 && m < 2) continue;
;                         const bf16x8 afr = *(const bf16x8*)(sm + LDS_MM + (rl * 64 + m * 16 + l15) * RS_T + (ks * 32 + quad * 8) * 2);
;                         yacc[m] = __builtin_amdgcn_mfma_f32_16x16x32_bf16(afr, xdt[ks], yacc[m], 0, 0, 0);
;                     }
;                 const float dec = e1L[rl * 64 + 63];
; #pragma unroll
;                 for (int n = 0; n < 8; ++n) {
;                     st[n] *= dec;
; #pragma unroll
;                     for (int ks = 0; ks < 2; ++ks) { const bf16x8 afr = *(const bf16x8*)(sm + L_BT + (n * 16 + l15) * RS_T + (((ks * 16 + quad * 4) ^ (4 * n)) * 4));
;                         st[n] = __builtin_amdgcn_mfma_f32_16x16x32_bf16(afr, xdd[ks], st[n], 0, 0, 0); }
;                 }
;             }
;             if (c + 1 < 32) { load_raw(zc + 64 * LDZ + 2048 + colb, toff, false, 2 * lp, rb); load_raw(zc + 64 * LDZ + 2048 + colc, toff, false, 2 * lp, rc); }
	ds_read_b128 v[120:123], v220
	s_waitcnt lgkmcnt(0)
	v_mfma_f32_16x16x32_bf16 v[108:111], v[120:123], v[132:135], v[108:111]
	ds_read_b128 v[120:123], v220 offset:2304
	v_mul_f32_e32 v241, v241, v182
	v_mul_f32_e32 v124, v124, v139
	s_waitcnt lgkmcnt(0)
	v_mfma_f32_16x16x32_bf16 v[112:115], v[120:123], v[132:135], v[112:115]
	ds_read_b128 v[120:123], v220 offset:4608
	v_mul_f32_e32 v144, v238, v251
	v_mul_f32_e32 v139, v242, v139
	s_waitcnt lgkmcnt(0)
	v_mfma_f32_16x16x32_bf16 v[116:119], v[120:123], v[132:135], v[116:119]
	ds_read_b128 v[120:123], v220 offset:6912
	v_mul_f32_e32 v145, v246, v251
	v_mul_f32_e32 v125, v125, v170
	s_waitcnt lgkmcnt(0)
	v_mfma_f32_16x16x32_bf16 v[128:131], v[120:123], v[132:135], v[128:131]
	ds_read_b128 v[120:123], v220 offset:4672
	v_mul_f32_e32 v242, v239, v252
	v_mul_f32_e32 v126, v126, v237
	v_mul_f32_e32 v246, v240, v253
	v_mul_f32_e32 v127, v127, v250
	v_cvt_pk_bf16_f32 v238, v124, v125
	v_cvt_pk_bf16_f32 v239, v126, v127
	v_cvt_pk_bf16_f32 v240, v144, v242
	v_cvt_pk_bf16_f32 v241, v246, v241
	v_mul_f32_e32 v170, v243, v170
	s_waitcnt lgkmcnt(0)
	v_mfma_f32_16x16x32_bf16 v[120:123], v[120:123], v[238:241], v[116:119]
	ds_read_b128 v[116:119], v220 offset:6976
	v_mul_f32_e32 v243, v247, v252
	v_mul_f32_e32 v237, v244, v237
	v_mul_f32_e32 v244, v248, v253
	s_waitcnt lgkmcnt(0)
	v_mfma_f32_16x16x32_bf16 v[116:119], v[116:119], v[238:241], v[128:131]
	ds_read_b32 v128, v203
	s_nop 2
	v_mul_f32_e32 v245, v245, v250
	v_mul_f32_e32 v182, v249, v182
	v_cvt_pk_bf16_f32 v124, v139, v170
	v_cvt_pk_bf16_f32 v125, v237, v245
	s_waitcnt lgkmcnt(0)
	v_pk_mul_f32 v[74:75], v[74:75], v[128:129] op_sel_hi:[1,0]
	v_pk_mul_f32 v[72:73], v[72:73], v[128:129] op_sel_hi:[1,0]
	v_add_u32_e32 v129, v205, v188
	ds_read_b128 v[130:133], v129 offset:34816
	ds_read_b128 v[238:241], v129 offset:34880
	ds_read_b128 v[246:249], v221 offset:37120
	ds_read_b128 v[250:253], v221 offset:37184
	s_waitcnt lgkmcnt(3)
	v_mfma_f32_16x16x32_bf16 v[72:75], v[130:133], v[104:107], v[72:75]
	ds_read_b128 v[130:133], v222 offset:39424
	v_cvt_pk_bf16_f32 v126, v145, v243
	v_cvt_pk_bf16_f32 v127, v244, v182
	ds_read_b128 v[242:245], v222 offset:39488
	v_pk_mul_f32 v[78:79], v[78:79], v[128:129] op_sel_hi:[1,0]
	s_waitcnt lgkmcnt(4)
	v_mfma_f32_16x16x32_bf16 v[72:75], v[238:241], v[124:127], v[72:75]
	ds_read_b128 v[238:241], v223 offset:41728
	v_pk_mul_f32 v[76:77], v[76:77], v[128:129] op_sel_hi:[1,0]
	v_pk_mul_f32 v[66:67], v[66:67], v[128:129] op_sel_hi:[1,0]
	v_pk_mul_f32 v[64:65], v[64:65], v[128:129] op_sel_hi:[1,0]
	s_waitcnt lgkmcnt(4)
	v_mfma_f32_16x16x32_bf16 v[76:79], v[246:249], v[104:107], v[76:79]
	ds_read_b128 v[246:249], v223 offset:41792
	v_pk_mul_f32 v[70:71], v[70:71], v[128:129] op_sel_hi:[1,0]
	v_pk_mul_f32 v[68:69], v[68:69], v[128:129] op_sel_hi:[1,0]
	s_waitcnt lgkmcnt(4)
	v_mfma_f32_16x16x32_bf16 v[76:79], v[250:253], v[124:127], v[76:79]
	ds_read_b128 v[250:253], v129 offset:44096
	v_pk_mul_f32 v[94:95], v[94:95], v[128:129] op_sel_hi:[1,0]
	v_pk_mul_f32 v[92:93], v[92:93], v[128:129] op_sel_hi:[1,0]
	s_waitcnt lgkmcnt(4)
	v_mfma_f32_16x16x32_bf16 v[64:67], v[130:133], v[104:107], v[64:67]
	ds_read_b128 v[130:133], v129 offset:44032
	v_pk_mul_f32 v[82:83], v[82:83], v[128:129] op_sel_hi:[1,0]
	v_pk_mul_f32 v[80:81], v[80:81], v[128:129] op_sel_hi:[1,0]
	s_waitcnt lgkmcnt(4)
	v_mfma_f32_16x16x32_bf16 v[64:67], v[242:245], v[124:127], v[64:67]
	ds_read_b128 v[242:245], v221 offset:46400
	v_pk_mul_f32 v[86:87], v[86:87], v[128:129] op_sel_hi:[1,0]
	v_pk_mul_f32 v[84:85], v[84:85], v[128:129] op_sel_hi:[1,0]
	s_waitcnt lgkmcnt(4)
	v_mfma_f32_16x16x32_bf16 v[68:71], v[238:241], v[104:107], v[68:71]
	ds_read_b128 v[238:241], v221 offset:46336
	v_pk_mul_f32 v[90:91], v[90:91], v[128:129] op_sel_hi:[1,0]
	v_pk_mul_f32 v[88:89], v[88:89], v[128:129] op_sel_hi:[1,0]
	s_waitcnt lgkmcnt(4)
	v_mfma_f32_16x16x32_bf16 v[68:71], v[246:249], v[124:127], v[68:71]
	ds_read_b128 v[246:249], v222 offset:48704
	s_waitcnt lgkmcnt(4)
	v_mfma_f32_16x16x32_bf16 v[92:95], v[250:253], v[104:107], v[92:95]
	ds_read_b128 v[250:253], v222 offset:48640
	s_waitcnt lgkmcnt(4)
	v_mfma_f32_16x16x32_bf16 v[92:95], v[130:133], v[124:127], v[92:95]
	ds_read_b128 v[128:131], v223 offset:51008
	s_waitcnt lgkmcnt(3)
	v_mfma_f32_16x16x32_bf16 v[80:83], v[242:245], v[104:107], v[80:83]
	v_mfma_f32_16x16x32_bf16 v[80:83], v[238:241], v[124:127], v[80:83]
	ds_read_b128 v[240:243], v223 offset:50944
	s_waitcnt lgkmcnt(1)
	v_mfma_f32_16x16x32_bf16 v[84:87], v[246:249], v[104:107], v[84:87]
	v_mfma_f32_16x16x32_bf16 v[84:87], v[250:253], v[124:127], v[84:87]
	v_mfma_f32_16x16x32_bf16 v[88:91], v[128:131], v[104:107], v[88:91]
	s_waitcnt lgkmcnt(0)
	v_mfma_f32_16x16x32_bf16 v[88:91], v[240:243], v[124:127], v[88:91]
	s_cbranch_vccnz .Lssd_drain
	v_lshl_add_u64 v[40:41], s[66:67], 0, v[176:177]
	v_add_co_u32_e32 v20, vcc, 0x64d6000, v40
	s_nop 1
	v_addc_co_u32_e32 v21, vcc, 0, v41, vcc
	v_add_co_u32_e32 v28, vcc, 0x64d9000, v40
	s_nop 1
	v_addc_co_u32_e32 v29, vcc, 0, v41, vcc
	v_add_co_u32_e32 v32, vcc, 0x64dc000, v40
	global_load_dwordx4 v[20:23], v[20:21], off offset:3712
	s_nop 0
	global_load_dwordx4 v[28:31], v[28:29], off offset:3840
	v_addc_co_u32_e32 v33, vcc, 0, v41, vcc
	v_add_co_u32_e32 v44, vcc, 0x64e0000, v40
	s_nop 1
	v_addc_co_u32_e32 v45, vcc, 0, v41, vcc
	v_add_co_u32_e32 v60, vcc, 0x64e3000, v40
	global_load_dwordx4 v[32:35], v[32:33], off offset:3968
	s_nop 0
	global_load_dwordx4 v[36:39], v[44:45], off
	v_addc_co_u32_e32 v61, vcc, 0, v41, vcc
	v_add_co_u32_e32 v46, vcc, 0x64d7000, v40
	s_nop 1
	v_addc_co_u32_e32 v47, vcc, 0, v41, vcc
	v_add_co_u32_e32 v42, vcc, 0x64da000, v40
	s_nop 1
	v_addc_co_u32_e32 v43, vcc, 0, v41, vcc
	v_add_co_u32_e32 v40, vcc, 0x64dd000, v40
	s_nop 1
	v_addc_co_u32_e32 v41, vcc, 0, v41, vcc
	global_load_dwordx4 v[48:51], v[42:43], off offset:1792
	global_load_dwordx4 v[52:55], v[40:41], off offset:1920
	s_nop 0
	global_load_dwordx4 v[40:43], v[60:61], off offset:128
	global_load_dwordx4 v[56:59], v[44:45], off offset:2048
	s_nop 0
	global_load_dwordx4 v[44:47], v[46:47], off offset:1664
	s_nop 0
	global_load_dwordx4 v[60:63], v[60:61], off offset:2176
; __device__ __forceinline__ void phase_ssd(const Params& p, uchar* sm, int j, bf16_t* zx, const float* dtraw, float* ssqb) {
;     ...
;             __syncthreads();
; #pragma unroll
;             for (int m = 0; m < 4; ++m)
; #pragma unroll
;                 for (int r = 0; r < 4; ++r) *(float*)(sm + (m * 16 + quad * 4 + r) * RS_Y + (chl + l15) * 4) = yacc[m][r];
;             __syncthreads();
.LBB0_479:
	v_add_u32_e32 v104, 0x400, v224
	s_barrier
	ds_write2_b32 v104, v110, v111 offset0:8 offset1:140
	v_add_u32_e32 v104, 0x2000, v224
	ds_write2_b32 v104, v112, v113 offset0:64 offset1:196
	v_add_u32_e32 v104, 0x2400, v224
	ds_write2_b32 v104, v114, v115 offset0:72 offset1:204
	v_add_u32_e32 v104, 0x4200, v224
	ds_write2_b32 v104, v120, v121 offset1:132
	v_add_u32_e32 v104, 0x4600, v224
	ds_write2_b32 v104, v122, v123 offset0:8 offset1:140
	v_add_u32_e32 v104, 0x6200, v224
	ds_write2_b32 v104, v116, v117 offset0:64 offset1:196
	v_add_u32_e32 v104, 0x6600, v224
	s_waitcnt vmcnt(11)
	v_lshlrev_b32_e32 v112, 16, v100
	ds_write2_b32 v104, v118, v119 offset0:72 offset1:204
	v_mul_f32_e32 v104, 0xbfb8aa3b, v112
	v_exp_f32_e32 v114, v104
	ds_write2_b32 v224, v108, v109 offset1:132
	s_waitcnt lgkmcnt(0)
	s_barrier
; __device__ __forceinline__ u32x4 pack8(const float (&o)[8]) { u32x4 r; r.x = pk2(o[0], o[1]); r.y = pk2(o[2], o[3]); r.z = pk2(o[4], o[5]); r.w = pk2(o[6], o[7]); return r; }
; __device__ __forceinline__ float silu_f(float v) { return v * __builtin_amdgcn_rcpf(1.f + __expf(-v)); }
; __device__ __forceinline__ void phase_ssd(const Params& p, uchar* sm, int j, bf16_t* zx, const float* dtraw, float* ssqb) {
;     ...
;                 float zf[8], o[8], xf[8];
;                 const f32x4 y0 = *(const f32x4*)(sm + (2 * lp) * RS_Y + c8 * 32), y1 = *(const f32x4*)(sm + (2 * lp) * RS_Y + c8 * 32 + 16);
;                 unpack8(z0, zf); unpack8(xp0, xf);
; #pragma unroll
;                 for (int i = 0; i < 4; ++i) { o[i] = (y0[i] + dskip * xf[i]) * silu_f(zf[i]); o[4 + i] = (y1[i] + dskip * xf[4 + i]) * silu_f(zf[4 + i]); }
;                 *(u32x4*)(zc + colx + toff) = pack8(o);
;                 float q0 = 0.f;
; #pragma unroll
;                 for (int i = 0; i < 8; ++i) q0 += o[i] * o[i];
;                 const f32x4 y2 = *(const f32x4*)(sm + (2 * lp + 1) * RS_Y + c8 * 32), y3 = *(const f32x4*)(sm + (2 * lp + 1) * RS_Y + c8 * 32 + 16);
;                 unpack8(z1, zf); unpack8(xp1, xf);
; #pragma unroll
;                 for (int i = 0; i < 4; ++i) { o[i] = (y2[i] + dskip * xf[i]) * silu_f(zf[i]); o[4 + i] = (y3[i] + dskip * xf[4 + i]) * silu_f(zf[4 + i]); }
;                 *(u32x4*)(zc + colx + LDZ + toff) = pack8(o);
;                 float q1 = 0.f;
; #pragma unroll
;                 for (int i = 0; i < 8; ++i) q1 += o[i] * o[i];
; #pragma unroll
;                 for (int sft = 1; sft < 16; sft <<= 1) { q0 += __shfl_xor(q0, sft); q1 += __shfl_xor(q1, sft); }
;                 if (c8 == 0) { float* sq = ssqb + (size_t)(zrow0 + 2 * lp) * 16 + g * 2 + hp; sq[0] = q0; sq[16] = q1; }
	ds_read_b128 v[104:107], v225
	ds_read_b128 v[108:111], v225 offset:16
	v_add_f32_e32 v114, 1.0, v114
	v_rcp_f32_e32 v170, v114
	v_lshlrev_b32_e32 v114, 16, v102
	v_lshlrev_b32_e32 v113, 16, v235
	v_mul_f32_e32 v115, 0xbfb8aa3b, v114
	v_exp_f32_e32 v115, v115
	v_pk_mul_f32 v[112:113], v[170:171], v[112:113]
	s_waitcnt lgkmcnt(1)
	v_add_f32_e32 v104, v113, v104
	v_mul_f32_e32 v116, v112, v104
	v_and_b32_e32 v112, 0xffff0000, v100
	v_mul_f32_e32 v100, 0xbfb8aa3b, v112
	v_add_f32_e32 v104, 1.0, v115
	v_exp_f32_e32 v100, v100
	v_rcp_f32_e32 v170, v104
	v_lshlrev_b32_e32 v115, 16, v236
	v_and_b32_e32 v104, 0xffff0000, v102
	v_add_f32_e32 v100, 1.0, v100
	v_pk_mul_f32 v[114:115], v[170:171], v[114:115]
	v_rcp_f32_e32 v170, v100
	v_mul_f32_e32 v100, 0xbfb8aa3b, v104
	v_exp_f32_e32 v100, v100
	v_and_b32_e32 v113, 0xffff0000, v235
	s_waitcnt lgkmcnt(0)
	v_add_f32_e32 v108, v115, v108
	v_pk_mul_f32 v[112:113], v[170:171], v[112:113]
	v_add_f32_e32 v100, 1.0, v100
	v_mul_f32_e32 v114, v114, v108
	v_rcp_f32_e32 v170, v100
	v_add_f32_e32 v100, v113, v105
	v_lshlrev_b32_e32 v108, 16, v101
	v_mul_f32_e32 v112, v112, v100
	v_mul_f32_e32 v100, 0xbfb8aa3b, v108
	v_exp_f32_e32 v100, v100
	v_and_b32_e32 v105, 0xffff0000, v236
	v_pk_mul_f32 v[104:105], v[170:171], v[104:105]
	v_mul_f32_e32 v120, v112, v112
	v_add_f32_e32 v100, 1.0, v100
	v_add_f32_e32 v102, v105, v109
	v_rcp_f32_e32 v170, v100
	v_lshlrev_b32_e32 v100, 16, v103
	v_mul_f32_e32 v113, v104, v102
	v_mul_f32_e32 v102, 0xbfb8aa3b, v100
	v_exp_f32_e32 v102, v102
	v_lshlrev_b32_e32 v109, 16, v233
	v_pk_mul_f32 v[104:105], v[170:171], v[108:109]
	s_waitcnt vmcnt(10)
	v_lshlrev_b32_e32 v108, 16, v96
	v_add_f32_e32 v102, 1.0, v102
	v_rcp_f32_e32 v170, v102
	v_and_b32_e32 v102, 0xffff0000, v101
	v_add_f32_e32 v105, v105, v106
	v_mul_f32_e32 v101, 0xbfb8aa3b, v102
	v_mul_f32_e32 v115, v104, v105
	v_exp_f32_e32 v104, v101
	v_lshlrev_b32_e32 v101, 16, v234
	v_pk_mul_f32 v[100:101], v[170:171], v[100:101]
	v_lshlrev_b32_e32 v109, 16, v231
	v_add_f32_e32 v104, 1.0, v104
	v_rcp_f32_e32 v170, v104
	v_and_b32_e32 v104, 0xffff0000, v103
	v_mul_f32_e32 v103, 0xbfb8aa3b, v104
	ds_read_b128 v[124:127], v226
	v_exp_f32_e32 v105, v103
	v_add_f32_e32 v101, v101, v110
	v_and_b32_e32 v103, 0xffff0000, v233
	v_mul_f32_e32 v117, v100, v101
	v_pk_mul_f32 v[100:101], v[170:171], v[102:103]
	v_add_f32_e32 v102, 1.0, v105
	v_rcp_f32_e32 v170, v102
	v_add_f32_e32 v101, v101, v107
	v_and_b32_e32 v105, 0xffff0000, v234
	v_mul_f32_e32 v118, v100, v101
	v_pk_mul_f32 v[100:101], v[170:171], v[104:105]
	v_fmac_f32_e32 v120, v116, v116
	v_add_f32_e32 v101, v101, v111
	v_mul_f32_e32 v119, v100, v101
	v_mul_f32_e32 v100, 0xbfb8aa3b, v108
	v_exp_f32_e32 v110, v100
	ds_read_b128 v[104:107], v226 offset:16
	v_fmac_f32_e32 v120, v115, v115
	v_fmac_f32_e32 v120, v118, v118
	v_add_f32_e32 v110, 1.0, v110
	v_rcp_f32_e32 v170, v110
	v_lshlrev_b32_e32 v110, 16, v98
	v_mul_f32_e32 v111, 0xbfb8aa3b, v110
	v_exp_f32_e32 v111, v111
	v_pk_mul_f32 v[108:109], v[170:171], v[108:109]
	v_fmac_f32_e32 v120, v114, v114
	s_waitcnt lgkmcnt(1)
	v_add_f32_e32 v124, v109, v124
	v_mul_f32_e32 v121, v108, v124
	v_and_b32_e32 v108, 0xffff0000, v96
	v_mul_f32_e32 v96, 0xbfb8aa3b, v108
	v_add_f32_e32 v100, 1.0, v111
	v_exp_f32_e32 v96, v96
	v_rcp_f32_e32 v170, v100
	v_lshlrev_b32_e32 v111, 16, v232
	v_and_b32_e32 v100, 0xffff0000, v98
	v_add_f32_e32 v96, 1.0, v96
	v_pk_mul_f32 v[110:111], v[170:171], v[110:111]
	v_rcp_f32_e32 v170, v96
	v_mul_f32_e32 v96, 0xbfb8aa3b, v100
	v_exp_f32_e32 v96, v96
	v_and_b32_e32 v109, 0xffff0000, v231
	s_waitcnt lgkmcnt(0)
	v_add_f32_e32 v104, v111, v104
	v_pk_mul_f32 v[108:109], v[170:171], v[108:109]
	v_add_f32_e32 v96, 1.0, v96
	v_mul_f32_e32 v110, v110, v104
	v_rcp_f32_e32 v170, v96
	v_add_f32_e32 v96, v109, v125
	v_lshlrev_b32_e32 v104, 16, v97
	v_mul_f32_e32 v108, v108, v96
	v_mul_f32_e32 v96, 0xbfb8aa3b, v104
	v_exp_f32_e32 v96, v96
	v_and_b32_e32 v101, 0xffff0000, v232
	v_pk_mul_f32 v[100:101], v[170:171], v[100:101]
	v_fmac_f32_e32 v120, v113, v113
	v_add_f32_e32 v96, 1.0, v96
	v_add_f32_e32 v98, v101, v105
	v_rcp_f32_e32 v170, v96
	v_lshlrev_b32_e32 v96, 16, v99
	v_mul_f32_e32 v109, v100, v98
	v_mul_f32_e32 v98, 0xbfb8aa3b, v96
	v_exp_f32_e32 v98, v98
	v_lshlrev_b32_e32 v105, 16, v229
	v_pk_mul_f32 v[100:101], v[170:171], v[104:105]
	v_fmac_f32_e32 v120, v117, v117
	v_add_f32_e32 v98, 1.0, v98
	v_rcp_f32_e32 v170, v98
	v_and_b32_e32 v98, 0xffff0000, v97
	v_add_f32_e32 v101, v101, v126
	v_mul_f32_e32 v97, 0xbfb8aa3b, v98
	v_mul_f32_e32 v102, v100, v101
	v_exp_f32_e32 v100, v97
	v_lshlrev_b32_e32 v97, 16, v230
	v_pk_mul_f32 v[96:97], v[170:171], v[96:97]
	v_fmac_f32_e32 v120, v119, v119
	v_add_f32_e32 v100, 1.0, v100
	v_rcp_f32_e32 v170, v100
	v_and_b32_e32 v100, 0xffff0000, v99
	v_mul_f32_e32 v99, 0xbfb8aa3b, v100
	v_exp_f32_e32 v101, v99
	v_add_f32_e32 v97, v97, v106
	v_and_b32_e32 v99, 0xffff0000, v229
	v_mul_f32_e32 v104, v96, v97
	v_pk_mul_f32 v[96:97], v[170:171], v[98:99]
	v_add_f32_e32 v98, 1.0, v101
	v_rcp_f32_e32 v170, v98
	v_add_f32_e32 v97, v97, v127
	v_and_b32_e32 v101, 0xffff0000, v230
	v_mul_f32_e32 v103, v96, v97
	v_pk_mul_f32 v[96:97], v[170:171], v[100:101]
	s_nop 0
	v_add_f32_e32 v97, v97, v107
	v_mul_f32_e32 v105, v96, v97
	v_mul_f32_e32 v96, v108, v108
	v_fmac_f32_e32 v96, v121, v121
	v_fmac_f32_e32 v96, v102, v102
	v_fmac_f32_e32 v96, v103, v103
	v_fmac_f32_e32 v96, v110, v110
	v_fmac_f32_e32 v96, v109, v109
	v_fmac_f32_e32 v96, v104, v104
	v_fmac_f32_e32 v96, v105, v105
	v_cvt_pk_bf16_f32 v98, v114, v113
	v_cvt_pk_bf16_f32 v97, v115, v118
	v_add_f32_dpp v120, v120, v120 quad_perm:[1,0,3,2] row_mask:0xf bank_mask:0xf
	v_add_f32_dpp v106, v96, v96 quad_perm:[1,0,3,2] row_mask:0xf bank_mask:0xf
	v_cvt_pk_bf16_f32 v96, v116, v112
	v_cvt_pk_bf16_f32 v99, v117, v119
	v_add_f32_dpp v120, v120, v120 quad_perm:[2,3,0,1] row_mask:0xf bank_mask:0xf
	v_add_f32_dpp v106, v106, v106 quad_perm:[2,3,0,1] row_mask:0xf bank_mask:0xf
	global_store_dwordx4 v[180:181], v[96:99], off
	v_cvt_pk_bf16_f32 v100, v121, v108
	v_cvt_pk_bf16_f32 v101, v102, v103
	v_add_f32_dpp v120, v120, v120 row_half_mirror row_mask:0xf bank_mask:0xf
	v_add_f32_dpp v106, v106, v106 row_half_mirror row_mask:0xf bank_mask:0xf
	v_cvt_pk_bf16_f32 v102, v110, v109
	v_cvt_pk_bf16_f32 v103, v104, v105
	v_add_f32_dpp v120, v120, v120 row_mirror row_mask:0xf bank_mask:0xf
	v_add_f32_dpp v106, v106, v106 row_mirror row_mask:0xf bank_mask:0xf
	global_store_dwordx4 v[178:179], v[100:103], off
	s_and_saveexec_b64 s[0:1], s[24:25]
	s_cbranch_execz .LBB0_465
	v_lshl_add_u64 v[96:97], s[66:67], 0, v[172:173]
	v_add_co_u32_e32 v96, vcc, 0x1ec1c000, v96
	s_nop 1
	v_addc_co_u32_e32 v97, vcc, 0, v97, vcc
	global_store_dword v[96:97], v120, off
	global_store_dword v[96:97], v106, off offset:64
	s_branch .LBB0_465
